# the free barrier-4 shadow of workgroups 160..255 now hosts 96 WD0 transposes; only 80 WD0 items remain at the start of GU0 (one per workgroup 128..207)
# speedup vs baseline: 1.0076x; 1.0011x over previous
.Lb4a_join:
	s_mov_b64 exec, s[80:81]
	s_mov_b64 vcc, exec
	s_cbranch_vccz .LBB0_396
	s_add_i32 s0, s78, 0x1c0
	s_cmpk_gt_i32 s0, 0x2bf
	s_waitcnt lgkmcnt(0)
	s_barrier
	s_cbranch_scc1 .LBB0_395
	s_movk_i32 s1, 0x2100
	v_lshrrev_b32_e32 v20, 3, v149
	v_and_b32_e32 v4, 56, v144
	s_cmpk_eq_i32 s58, 0x100
	v_mad_u32_u24 v1, v148, s1, 0
	v_lshrrev_b32_e32 v0, 5, v149
	v_and_b32_e32 v2, 31, v168
	v_mul_u32_u24_e32 v3, 0x84, v4
	v_lshlrev_b32_e32 v7, 2, v20
	s_cselect_b64 s[6:7], -1, 0
	v_mov_b32_e32 v5, 0
	v_lshl_add_u32 v6, v2, 2, v1
	s_movk_i32 s1, 0x84
	v_add3_u32 v21, v1, v3, v7
	v_or_b32_e32 v22, 8, v20
	v_or_b32_e32 v23, 16, v20
	v_or_b32_e32 v24, 24, v20
	v_mov_b32_e32 v1, v0
	s_movk_i32 s2, 0x187f
	s_movk_i32 s3, 0x1ff
	s_movk_i32 s10, 0xcff
	v_lshlrev_b32_e32 v8, 2, v2
	v_lshlrev_b32_e32 v10, 1, v4
	v_mov_b32_e32 v25, 0xffffe780
	v_mov_b32_e32 v26, 0xc00
	v_mov_b32_e32 v27, 0x600
	v_mov_b32_e32 v28, 0x2c0000
	v_mov_b32_e32 v29, 0x1400000
	v_mov_b32_e32 v30, 0x2980000
	v_mov_b32_e32 v31, 0x900000
	v_mov_b32_e32 v32, 0x1e80000
	v_mov_b32_e32 v33, 0x700000
	v_mov_b32_e32 v34, 0x1c80000
	v_mov_b32_e32 v35, 0x100000
	v_mov_b32_e32 v36, 0x1980000
	s_branch .LBB0_379

.LBB0_396:
	s_waitcnt vmcnt(0)
	s_waitcnt lgkmcnt(0)
	s_barrier
	s_mov_b64 s[4:5], exec
	v_readlane_b32 s0, v219, 25
	v_readlane_b32 s1, v219, 26
	s_and_b64 s[0:1], s[4:5], s[0:1]
	s_mov_b64 exec, s[0:1]
	s_cbranch_execz .LBB0_448
	v_readlane_b32 s0, v219, 27
	v_readlane_b32 s1, v219, 28
	v_readlane_b32 s2, v219, 29
	v_readlane_b32 s3, v219, 30
	s_waitcnt vmcnt(0) lgkmcnt(0)
	s_cmp_ge_u32 s3, 0x100
	s_cbranch_scc1 .Lb4p_nol
	v_mov_b32_e32 v0, 1
	v_mov_b32_e32 v1, 0x10c0
	s_nop 3
	global_atomic_add v1, v0, s[0:1]

.Lgb6_done:
	v_mov_b32_e32 v1, 0x10c0
	s_mov_b32 s15, 0
.Lgb6_spin2:
	global_load_dword v2, v1, s[0:1] sc1
	s_waitcnt vmcnt(0)
	v_readfirstlane_b32 s13, v2
	s_nop 1
	s_cmp_ge_u32 s13, 256
	s_cbranch_scc1 .Lgb6_done2
	s_sleep 4
	s_add_i32 s15, s15, 1
	s_cmp_lt_u32 s15, 0x200000
	s_cbranch_scc1 .Lgb6_spin2
